# v35 without the prompt-loop early LDS write for map-1 waves (baseline write placement, counted waits kept out)
# baseline (speedup 1.0000x reference)
;     ...
;     for (int tt = 0; tt < NT; tt += 2) {
;         if (tt + 2 < NT) DA_ISSUE(pfB, tt + 2);
;         DA_COMPUTE(tt, 0);
;         if (tt + 1 < NT) DA_WRITE(pfA, tt + 1, 1);
;         __syncthreads();
;         if (tt + 1 >= NT) break;
;         if (tt + 3 < NT) DA_ISSUE(pfA, tt + 3);
;         DA_COMPUTE(tt + 1, 1);
;         if (tt + 2 < NT) DA_WRITE(pfB, tt + 2, 0);
;         __syncthreads();
;     }
.LBB0_925:
	s_add_i32 s15, s11, -3
	s_cmp_lt_u32 s15, s12
	s_cselect_b64 s[6:7], -1, 0
	s_cmp_ge_u32 s15, s12
	s_cbranch_scc1 .LBB0_927
	v_subrev_u32_e32 v66, 64, v150
	v_ashrrev_i32_e32 v67, 31, v66
	v_lshlrev_b64 v[66:67], 10, v[66:67]
	v_lshl_or_b32 v66, v148, 1, v66
	v_lshl_add_u64 v[68:69], s[72:73], 0, v[66:67]
	v_lshl_add_u64 v[66:67], s[74:75], 0, v[66:67]
	global_load_dwordx4 v[130:133], v[68:69], off offset:16
	global_load_dwordx4 v[134:137], v[68:69], off
	global_load_dwordx4 v[138:141], v[66:67], off offset:16
	global_load_dwordx4 v[142:145], v[66:67], off
.LBB0_927:
	s_cmp_ge_u32 s15, s14
	s_cbranch_scc1 .LBB0_931
	s_add_i32 s99, s15, 1
	s_cmp_ge_u32 s99, s14
	s_cbranch_scc1 .Lpf0_slow
	ds_read_b128 v[66:69], v162
	ds_read_b128 v[166:169], v162 offset:32
	ds_read_b128 v[82:85], v162 offset:4608
	ds_read_b128 v[176:179], v162 offset:4640
	v_cvt_f32_i32_e32 v186, v158
	s_waitcnt lgkmcnt(3)
	v_mfma_f32_32x32x16_bf16 v[66:81], v[66:69], v[110:113], v[210:225]
	v_mul_f32_e64 v175, -v153, v186
	s_waitcnt lgkmcnt(1)
	v_mfma_f32_32x32x16_bf16 v[82:97], v[82:85], v[110:113], v[226:241]
	v_mfma_f32_32x32x16_bf16 v[66:81], v[166:169], v[106:109], v[66:81]
	s_waitcnt lgkmcnt(0)
	v_mfma_f32_32x32x16_bf16 v[82:97], v[176:179], v[106:109], v[82:97]
	ds_read_b128 v[166:169], v162 offset:64
	ds_read_b128 v[176:179], v162 offset:96
	s_waitcnt lgkmcnt(1)
	v_mfma_f32_32x32x16_bf16 v[66:81], v[166:169], v[102:105], v[66:81]
	ds_read_b128 v[166:169], v162 offset:4672
	ds_read_b128 v[182:185], v162 offset:4704
	s_waitcnt lgkmcnt(1)
	v_mfma_f32_32x32x16_bf16 v[82:97], v[166:169], v[102:105], v[82:97]
	v_mfma_f32_32x32x16_bf16 v[66:81], v[176:179], v[98:101], v[66:81]
	s_waitcnt lgkmcnt(0)
	v_mfma_f32_32x32x16_bf16 v[82:97], v[182:185], v[98:101], v[82:97]
	ds_read_b64_tr_b16 v[166:167], v156 offset:18432
	ds_read_b64_tr_b16 v[168:169], v156 offset:20992
	ds_read_b64_tr_b16 v[176:177], v156 offset:18496
	ds_read_b64_tr_b16 v[178:179], v156 offset:21056
	ds_read_b64_tr_b16 v[180:181], v156 offset:18560
	ds_read_b64_tr_b16 v[182:183], v156 offset:21120
	ds_read_b64_tr_b16 v[184:185], v156 offset:18624
	ds_read_b64_tr_b16 v[186:187], v156 offset:21184
	s_nop 5
	v_max3_f32 v0, v66, v67, v68
	v_max3_f32 v151, v82, v83, v84
	v_max3_f32 v0, v0, v69, v70
	v_max3_f32 v151, v151, v85, v86
	v_max3_f32 v0, v0, v71, v72
	v_max3_f32 v151, v151, v87, v88
	v_max3_f32 v0, v0, v73, v74
	v_max3_f32 v151, v151, v89, v90
	v_max3_f32 v0, v0, v75, v76
	v_max3_f32 v151, v151, v91, v92
	v_max3_f32 v0, v0, v77, v78
	v_max3_f32 v151, v151, v93, v94
	v_max3_f32 v0, v0, v79, v80
	v_max3_f32 v151, v151, v95, v96
	v_max3_f32 v0, v0, v81, v151
	v_max_f32_e32 v0, v0, v97
	v_add_f32_e32 v0, v0, v175
	v_mov_b32_e32 v164, v0
	s_nop 1
	v_permlane32_swap_b32_e32 v164, v0
	s_nop 0
	v_max_f32_e32 v0, v0, v164
	v_add_f32_e32 v164, 0x41000000, v163
	v_cmp_gt_f32_e32 vcc, v0, v164
	s_cbranch_vccz .Lpf0_nores
	v_max_f32_e32 v0, v163, v0
	v_sub_f32_e32 v164, v163, v0
	v_exp_f32_e32 v164, v164
	v_mov_b32_e32 v163, v0
	s_nop 0
	v_mul_f32_e32 v159, v159, v164
	v_pk_mul_f32 v[64:65], v[64:65], v[164:165] op_sel_hi:[1,0]
	v_pk_mul_f32 v[62:63], v[62:63], v[164:165] op_sel_hi:[1,0]
	v_pk_mul_f32 v[60:61], v[60:61], v[164:165] op_sel_hi:[1,0]
	v_pk_mul_f32 v[58:59], v[58:59], v[164:165] op_sel_hi:[1,0]
	v_pk_mul_f32 v[56:57], v[56:57], v[164:165] op_sel_hi:[1,0]
	v_pk_mul_f32 v[54:55], v[54:55], v[164:165] op_sel_hi:[1,0]
	v_pk_mul_f32 v[52:53], v[52:53], v[164:165] op_sel_hi:[1,0]
	v_pk_mul_f32 v[50:51], v[50:51], v[164:165] op_sel_hi:[1,0]
	v_pk_mul_f32 v[48:49], v[48:49], v[164:165] op_sel_hi:[1,0]
	v_pk_mul_f32 v[46:47], v[46:47], v[164:165] op_sel_hi:[1,0]
	v_pk_mul_f32 v[44:45], v[44:45], v[164:165] op_sel_hi:[1,0]
	v_pk_mul_f32 v[42:43], v[42:43], v[164:165] op_sel_hi:[1,0]
	v_pk_mul_f32 v[40:41], v[40:41], v[164:165] op_sel_hi:[1,0]
	v_pk_mul_f32 v[38:39], v[38:39], v[164:165] op_sel_hi:[1,0]
	v_pk_mul_f32 v[36:37], v[36:37], v[164:165] op_sel_hi:[1,0]
	v_pk_mul_f32 v[34:35], v[34:35], v[164:165] op_sel_hi:[1,0]
	v_pk_mul_f32 v[32:33], v[32:33], v[164:165] op_sel_hi:[1,0]
	v_pk_mul_f32 v[30:31], v[30:31], v[164:165] op_sel_hi:[1,0]
	v_pk_mul_f32 v[28:29], v[28:29], v[164:165] op_sel_hi:[1,0]
	v_pk_mul_f32 v[26:27], v[26:27], v[164:165] op_sel_hi:[1,0]
	v_pk_mul_f32 v[24:25], v[24:25], v[164:165] op_sel_hi:[1,0]
	v_pk_mul_f32 v[22:23], v[22:23], v[164:165] op_sel_hi:[1,0]
	v_pk_mul_f32 v[20:21], v[20:21], v[164:165] op_sel_hi:[1,0]
	v_pk_mul_f32 v[18:19], v[18:19], v[164:165] op_sel_hi:[1,0]
	v_pk_mul_f32 v[16:17], v[16:17], v[164:165] op_sel_hi:[1,0]
	v_pk_mul_f32 v[14:15], v[14:15], v[164:165] op_sel_hi:[1,0]
	v_pk_mul_f32 v[12:13], v[12:13], v[164:165] op_sel_hi:[1,0]
	v_pk_mul_f32 v[10:11], v[10:11], v[164:165] op_sel_hi:[1,0]
	v_pk_mul_f32 v[8:9], v[8:9], v[164:165] op_sel_hi:[1,0]
	v_pk_mul_f32 v[6:7], v[6:7], v[164:165] op_sel_hi:[1,0]
	v_pk_mul_f32 v[4:5], v[4:5], v[164:165] op_sel_hi:[1,0]
	v_pk_mul_f32 v[2:3], v[2:3], v[164:165] op_sel_hi:[1,0]

;     ...
;         if (tt + 3 < NT) DA_ISSUE(pfA, tt + 3);
;         DA_COMPUTE(tt + 1, 1);
;         if (tt + 2 < NT) DA_WRITE(pfB, tt + 2, 0);
;         __syncthreads();
.Lpf1_end:
	s_andn2_b64 vcc, exec, s[6:7]
	s_cbranch_vccnz .LBB0_924
.LBB0_938:
	ds_write_b128 v154, v[134:137]
	ds_write_b128 v154, v[130:133] offset:16
	ds_write_b128 v155, v[142:145] offset:18432
	ds_write_b128 v155, v[138:141] offset:18448
	s_branch .LBB0_924
